# UP epilogue: first batch of conv-parameter loads issued at the top of the epilogue ahead of the seam-row stores, waited with a vmcnt equal to the number of seam stores the wave issued
# baseline (speedup 1.0000x reference)
; #define PG8_STAGE(bufoff, gbase, voff) do { _Pragma("unroll") for (int _i = 0; _i < 2; ++_i) \
;     __builtin_amdgcn_global_load_lds((const unsigned*)((const char*)(gbase) + (voff)[_i]), (LAS unsigned*)(lds + (bufoff) + ldsw + _i * 8192), 16, 0, 0); } while (0)
; #define PG8_LDA(dst, b, h) do { _Pragma("unroll") for (int m = 0; m < 4; ++m) _Pragma("unroll") for (int k = 0; k < 2; ++k) dst[m][k] = *(const LAS bf16x8*)(lds + PG8_SA(b, h) + aoff + m * 2048 + k * 1024); } while (0)
; #define PG8_LDB(dst, b, h) do { _Pragma("unroll") for (int n = 0; n < 2; ++n) _Pragma("unroll") for (int k = 0; k < 2; ++k) dst[n][k] = *(const LAS bf16x8*)(lds + PG8_SB(b, h) + boff + n * 2048 + k * 1024); } while (0)
; #define PG8_MMA(ai, bj, At, Bt) do { __builtin_amdgcn_s_setprio(1); _Pragma("unroll") for (int m = 0; m < 4; ++m) _Pragma("unroll") for (int n = 0; n < 2; ++n) _Pragma("unroll") for (int k = 0; k < 2; ++k) \
;     acc[ai][bj][m][n] = __builtin_amdgcn_mfma_f32_16x16x32_bf16(Bt[n][k], At[m][k], acc[ai][bj][m][n], 0, 0, 0); __builtin_amdgcn_s_setprio(0); } while (0)
; #define PG8_WAIT_L(n) asm volatile("s_waitcnt lgkmcnt(" #n ")" ::: "memory")
; #define PG8_BAR __builtin_amdgcn_s_barrier()
; #define PG8_SCHED __builtin_amdgcn_sched_barrier(0)
; template <class Epi>
; __device__ __forceinline__ void gemm_phase(LAS unsigned char* lds, const Gemm g, const StaticOrder& S, const Epi& E, int wv0) {
;     ...
;       PG8_LDB(B0, 0, 0); PG8_SCHED; PG8_LDA(At, 0, 0); PG8_STAGE(PG8_SA(1, 1), a1 + hstepA, voffA);
;       PG8_WAIT_L(8); PG8_BAR; PG8_WAIT_L(0); PG8_MMA(0, 0, At, B0); PG8_BAR; PG8_SCHED;
;       PG8_LDB(B1, 0, 1); PG8_STAGE(PG8_SB(0, 0), b2, voffB);
;       PG8_BAR; PG8_WAIT_L(0); PG8_MMA(0, 1, At, B1); PG8_BAR;
;       PG8_LDA(At, 0, 1); PG8_STAGE(PG8_SA(0, 0), a2, voffA);
;       PG8_BAR; PG8_WAIT_L(0); PG8_MMA(1, 0, At, B0); PG8_BAR; PG8_SCHED;
.LBB0_1270:
	s_add_u32 s0, s60, 0xfff80080
	s_addc_u32 s62, s61, -1
	s_add_i32 s80, 0, 0x10000
	v_add_u32_e32 v134, s80, v213
	ds_read_b128 v[122:125], v134
	ds_read_b128 v[126:129], v134 offset:1024
	ds_read_b128 v[130:133], v134 offset:2048
	ds_read_b128 v[134:137], v134 offset:3072
	s_cmp_eq_u32 s78, 28
	s_cselect_b32 s65, s1, s62
	s_cselect_b32 s64, s51, s0
	s_cselect_b32 s63, s49, s75
	s_cselect_b32 s62, s57, s59
	v_lshl_add_u64 v[192:193], s[60:61], 0, v[172:173]
	s_add_i32 m0, s77, 0xc000
	ds_read_b128 v[138:141], v225
	ds_read_b128 v[142:145], v225 offset:1024
	ds_read_b128 v[146:149], v225 offset:2048
	ds_read_b128 v[150:153], v225 offset:3072
	ds_read_b128 v[176:179], v225 offset:4096
	ds_read_b128 v[180:183], v225 offset:5120
	ds_read_b128 v[184:187], v225 offset:6144
	ds_read_b128 v[188:191], v225 offset:7168
	global_load_lds_dwordx4 v[192:193], off
	v_lshl_add_u64 v[192:193], s[60:61], 0, v[174:175]
	s_add_i32 m0, s77, 0xe000
	s_nop 0
	global_load_lds_dwordx4 v[192:193], off
	s_waitcnt lgkmcnt(8)
	s_barrier
	s_waitcnt lgkmcnt(0)
	s_setprio 1
	s_waitcnt lgkmcnt(0)
	v_mfma_f32_16x16x32_bf16 v[158:161], v[122:125], v[138:141], v[158:161]
	v_mfma_f32_16x16x32_bf16 v[60:63], v[130:133], v[138:141], v[60:63]
	v_mfma_f32_16x16x32_bf16 v[118:121], v[122:125], v[146:149], v[118:121]
	v_mfma_f32_16x16x32_bf16 v[52:55], v[130:133], v[146:149], v[52:55]
	v_mfma_f32_16x16x32_bf16 v[110:113], v[122:125], v[176:179], v[110:113]
	v_mfma_f32_16x16x32_bf16 v[44:47], v[130:133], v[176:179], v[44:47]
	v_mfma_f32_16x16x32_bf16 v[106:109], v[122:125], v[184:187], v[106:109]
	v_mfma_f32_16x16x32_bf16 v[40:43], v[130:133], v[184:187], v[40:43]
	v_mfma_f32_16x16x32_bf16 v[158:161], v[126:129], v[142:145], v[158:161]
	v_mfma_f32_16x16x32_bf16 v[60:63], v[134:137], v[142:145], v[60:63]
	v_mfma_f32_16x16x32_bf16 v[118:121], v[126:129], v[150:153], v[118:121]
	v_mfma_f32_16x16x32_bf16 v[52:55], v[134:137], v[150:153], v[52:55]
	v_mfma_f32_16x16x32_bf16 v[110:113], v[126:129], v[180:183], v[110:113]
	v_mfma_f32_16x16x32_bf16 v[44:47], v[134:137], v[180:183], v[44:47]
	v_mfma_f32_16x16x32_bf16 v[106:109], v[126:129], v[188:191], v[106:109]
	v_mfma_f32_16x16x32_bf16 v[40:43], v[134:137], v[188:191], v[40:43]
	s_setprio 0
	s_barrier
	s_add_i32 s0, 0, 0x14000
	s_add_i32 s80, s80, s76
	v_add_u32_e32 v204, s0, v213
	v_lshl_add_u64 v[208:209], s[62:63], 0, v[96:97]
	s_mov_b32 m0, s80
	ds_read_b128 v[192:195], v204
	ds_read_b128 v[196:199], v204 offset:1024
	ds_read_b128 v[200:203], v204 offset:2048
	ds_read_b128 v[204:207], v204 offset:3072
	global_load_lds_dwordx4 v[208:209], off
	v_lshl_add_u64 v[210:211], s[62:63], 0, v[166:167]
	s_add_i32 m0, s80, 0x2000
	s_nop 0
	global_load_lds_dwordx4 v[210:211], off
	s_barrier
	s_waitcnt lgkmcnt(0)
	s_setprio 1
	s_waitcnt lgkmcnt(0)
	v_mfma_f32_16x16x32_bf16 v[154:157], v[192:195], v[138:141], v[154:157]
	v_mfma_f32_16x16x32_bf16 v[56:59], v[200:203], v[138:141], v[56:59]
	v_mfma_f32_16x16x32_bf16 v[114:117], v[192:195], v[146:149], v[114:117]
	v_mfma_f32_16x16x32_bf16 v[48:51], v[200:203], v[146:149], v[48:51]
	v_mfma_f32_16x16x32_bf16 v[102:105], v[192:195], v[176:179], v[102:105]
	v_mfma_f32_16x16x32_bf16 v[36:39], v[200:203], v[176:179], v[36:39]
	v_mfma_f32_16x16x32_bf16 v[98:101], v[192:195], v[184:187], v[98:101]
	v_mfma_f32_16x16x32_bf16 v[32:35], v[200:203], v[184:187], v[32:35]
	v_mfma_f32_16x16x32_bf16 v[154:157], v[196:199], v[142:145], v[154:157]
	v_mfma_f32_16x16x32_bf16 v[56:59], v[204:207], v[142:145], v[56:59]
	v_mfma_f32_16x16x32_bf16 v[114:117], v[196:199], v[150:153], v[114:117]
	v_mfma_f32_16x16x32_bf16 v[48:51], v[204:207], v[150:153], v[48:51]
	v_mfma_f32_16x16x32_bf16 v[102:105], v[196:199], v[180:183], v[102:105]
	v_mfma_f32_16x16x32_bf16 v[36:39], v[204:207], v[180:183], v[36:39]
	v_mfma_f32_16x16x32_bf16 v[98:101], v[196:199], v[188:191], v[98:101]
	v_mfma_f32_16x16x32_bf16 v[32:35], v[204:207], v[188:191], v[32:35]
	s_setprio 0
	s_mov_b32 m0, s77
	v_lshl_add_u64 v[220:221], s[64:65], 0, v[162:163]
	s_barrier
	ds_read_b128 v[138:141], v225 offset:16384
	ds_read_b128 v[142:145], v225 offset:17408
	ds_read_b128 v[146:149], v225 offset:18432
	ds_read_b128 v[150:153], v225 offset:19456
	ds_read_b128 v[176:179], v225 offset:20480
	ds_read_b128 v[180:183], v225 offset:21504
	ds_read_b128 v[184:187], v225 offset:22528
	ds_read_b128 v[188:191], v225 offset:23552
	global_load_lds_dwordx4 v[220:221], off
	v_lshl_add_u64 v[222:223], s[64:65], 0, v[164:165]
	s_mov_b32 m0, s86
	s_nop 0
	global_load_lds_dwordx4 v[222:223], off
	s_barrier
	s_waitcnt lgkmcnt(0)
	s_setprio 1
	s_waitcnt lgkmcnt(0)
	v_mfma_f32_16x16x32_bf16 v[92:95], v[122:125], v[138:141], v[92:95]
	v_mfma_f32_16x16x32_bf16 v[28:31], v[130:133], v[138:141], v[28:31]
	v_mfma_f32_16x16x32_bf16 v[84:87], v[122:125], v[146:149], v[84:87]
	v_mfma_f32_16x16x32_bf16 v[20:23], v[130:133], v[146:149], v[20:23]
	v_mfma_f32_16x16x32_bf16 v[76:79], v[122:125], v[176:179], v[76:79]
	v_mfma_f32_16x16x32_bf16 v[12:15], v[130:133], v[176:179], v[12:15]
	v_mfma_f32_16x16x32_bf16 v[72:75], v[122:125], v[184:187], v[72:75]
	v_mfma_f32_16x16x32_bf16 v[8:11], v[130:133], v[184:187], v[8:11]
	v_mfma_f32_16x16x32_bf16 v[92:95], v[126:129], v[142:145], v[92:95]
	v_mfma_f32_16x16x32_bf16 v[28:31], v[134:137], v[142:145], v[28:31]
	v_mfma_f32_16x16x32_bf16 v[84:87], v[126:129], v[150:153], v[84:87]
	v_mfma_f32_16x16x32_bf16 v[20:23], v[134:137], v[150:153], v[20:23]
	v_mfma_f32_16x16x32_bf16 v[76:79], v[126:129], v[180:183], v[76:79]
	v_mfma_f32_16x16x32_bf16 v[12:15], v[134:137], v[180:183], v[12:15]
	v_mfma_f32_16x16x32_bf16 v[72:75], v[126:129], v[188:191], v[72:75]
	v_mfma_f32_16x16x32_bf16 v[8:11], v[134:137], v[188:191], v[8:11]
	s_setprio 0
	s_barrier
; #define PG8_STAGE(bufoff, gbase, voff) do { _Pragma("unroll") for (int _i = 0; _i < 2; ++_i) \
;     __builtin_amdgcn_global_load_lds((const unsigned*)((const char*)(gbase) + (voff)[_i]), (LAS unsigned*)(lds + (bufoff) + ldsw + _i * 8192), 16, 0, 0); } while (0)
; #define PG8_LDA(dst, b, h) do { _Pragma("unroll") for (int m = 0; m < 4; ++m) _Pragma("unroll") for (int k = 0; k < 2; ++k) dst[m][k] = *(const LAS bf16x8*)(lds + PG8_SA(b, h) + aoff + m * 2048 + k * 1024); } while (0)
; #define PG8_LDB(dst, b, h) do { _Pragma("unroll") for (int n = 0; n < 2; ++n) _Pragma("unroll") for (int k = 0; k < 2; ++k) dst[n][k] = *(const LAS bf16x8*)(lds + PG8_SB(b, h) + boff + n * 2048 + k * 1024); } while (0)
; #define PG8_MMA(ai, bj, At, Bt) do { __builtin_amdgcn_s_setprio(1); _Pragma("unroll") for (int m = 0; m < 4; ++m) _Pragma("unroll") for (int n = 0; n < 2; ++n) _Pragma("unroll") for (int k = 0; k < 2; ++k) \
;     acc[ai][bj][m][n] = __builtin_amdgcn_mfma_f32_16x16x32_bf16(Bt[n][k], At[m][k], acc[ai][bj][m][n], 0, 0, 0); __builtin_amdgcn_s_setprio(0); } while (0)
; #define PG8_WAIT_V(n) asm volatile("s_waitcnt vmcnt(" #n ")" ::: "memory")
; #define PG8_WAIT_L(n) asm volatile("s_waitcnt lgkmcnt(" #n ")" ::: "memory")
; #define PG8_BAR __builtin_amdgcn_s_barrier()
; #define PG8_SCHED __builtin_amdgcn_sched_barrier(0)
; template <class Epi>
; __device__ __forceinline__ void gemm_phase(LAS unsigned char* lds, const Gemm g, const StaticOrder& S, const Epi& E, int wv0) {
;     ...
;       PG8_STAGE(PG8_SB(0, 1), b2 + hstepB, voffB);
;       PG8_WAIT_V(6); PG8_BAR; PG8_MMA(1, 1, At, B1); PG8_BAR;
;       PG8_LDB(B0, 1, 0); PG8_SCHED; PG8_LDA(At, 1, 0); PG8_STAGE(PG8_SA(0, 1), a2 + hstepA, voffA);
;       PG8_WAIT_L(8); PG8_BAR; PG8_WAIT_L(0); PG8_MMA(0, 0, At, B0); PG8_BAR; PG8_SCHED;
;       PG8_LDB(B1, 1, 1); PG8_STAGE(PG8_SB(1, 0), b3, voffB);
;       PG8_BAR; PG8_WAIT_L(0); PG8_MMA(0, 1, At, B1); PG8_BAR;
	s_add_u32 vcc_lo, s62, 0x80000
	s_addc_u32 vcc_hi, s63, 0
	s_add_i32 s0, s0, s76
	v_lshl_add_u64 v[122:123], vcc, 0, v[96:97]
	s_mov_b32 m0, s0
	s_nop 0
	global_load_lds_dwordx4 v[122:123], off
	v_lshl_add_u64 v[122:123], vcc, 0, v[166:167]
	s_add_i32 m0, s0, 0x2000
	s_nop 0
	global_load_lds_dwordx4 v[122:123], off
	s_waitcnt vmcnt(6)
	s_barrier
	s_setprio 1
	v_mfma_f32_16x16x32_bf16 v[88:91], v[192:195], v[138:141], v[88:91]
	v_mfma_f32_16x16x32_bf16 v[24:27], v[200:203], v[138:141], v[24:27]
	v_mfma_f32_16x16x32_bf16 v[80:83], v[192:195], v[146:149], v[80:83]
	v_mfma_f32_16x16x32_bf16 v[16:19], v[200:203], v[146:149], v[16:19]
	v_mfma_f32_16x16x32_bf16 v[68:71], v[192:195], v[176:179], v[68:71]
	v_mfma_f32_16x16x32_bf16 v[4:7], v[200:203], v[176:179], v[4:7]
	v_mfma_f32_16x16x32_bf16 v[64:67], v[192:195], v[184:187], v[64:67]
	v_mfma_f32_16x16x32_bf16 v[0:3], v[200:203], v[184:187], v[0:3]
	v_mfma_f32_16x16x32_bf16 v[88:91], v[196:199], v[142:145], v[88:91]
	v_mfma_f32_16x16x32_bf16 v[24:27], v[204:207], v[142:145], v[24:27]
	v_mfma_f32_16x16x32_bf16 v[80:83], v[196:199], v[150:153], v[80:83]
	v_mfma_f32_16x16x32_bf16 v[16:19], v[204:207], v[150:153], v[16:19]
	v_mfma_f32_16x16x32_bf16 v[68:71], v[196:199], v[180:183], v[68:71]
	v_mfma_f32_16x16x32_bf16 v[4:7], v[204:207], v[180:183], v[4:7]
	v_mfma_f32_16x16x32_bf16 v[64:67], v[196:199], v[188:191], v[64:67]
	v_mfma_f32_16x16x32_bf16 v[0:3], v[204:207], v[188:191], v[0:3]
	s_setprio 0
	s_add_i32 s0, 0, 0x18000
	v_add_u32_e32 v134, s0, v213
	s_barrier
	ds_read_b128 v[122:125], v134
	ds_read_b128 v[126:129], v134 offset:1024
	ds_read_b128 v[130:133], v134 offset:2048
	ds_read_b128 v[134:137], v134 offset:3072
	s_add_u32 s64, s64, 0x80000
	s_addc_u32 s65, s65, 0
	s_mov_b32 m0, s87
	v_lshl_add_u64 v[192:193], s[64:65], 0, v[162:163]
	ds_read_b128 v[138:141], v225 offset:32768
	ds_read_b128 v[142:145], v225 offset:33792
	ds_read_b128 v[146:149], v225 offset:34816
	ds_read_b128 v[150:153], v225 offset:35840
	ds_read_b128 v[176:179], v225 offset:36864
	ds_read_b128 v[180:183], v225 offset:37888
	ds_read_b128 v[184:187], v225 offset:38912
	ds_read_b128 v[188:191], v225 offset:39936
	global_load_lds_dwordx4 v[192:193], off
	v_lshl_add_u64 v[192:193], s[64:65], 0, v[164:165]
	s_mov_b32 m0, s88
	s_nop 0
	global_load_lds_dwordx4 v[192:193], off
	s_waitcnt lgkmcnt(8)
	s_barrier
	s_waitcnt lgkmcnt(0)
	s_setprio 1
	s_waitcnt lgkmcnt(0)
	v_mfma_f32_16x16x32_bf16 v[158:161], v[122:125], v[138:141], v[158:161]
	v_mfma_f32_16x16x32_bf16 v[60:63], v[130:133], v[138:141], v[60:63]
	v_mfma_f32_16x16x32_bf16 v[118:121], v[122:125], v[146:149], v[118:121]
	v_mfma_f32_16x16x32_bf16 v[52:55], v[130:133], v[146:149], v[52:55]
	v_mfma_f32_16x16x32_bf16 v[110:113], v[122:125], v[176:179], v[110:113]
	v_mfma_f32_16x16x32_bf16 v[44:47], v[130:133], v[176:179], v[44:47]
	v_mfma_f32_16x16x32_bf16 v[106:109], v[122:125], v[184:187], v[106:109]
	v_mfma_f32_16x16x32_bf16 v[40:43], v[130:133], v[184:187], v[40:43]
	v_mfma_f32_16x16x32_bf16 v[158:161], v[126:129], v[142:145], v[158:161]
	v_mfma_f32_16x16x32_bf16 v[60:63], v[134:137], v[142:145], v[60:63]
	v_mfma_f32_16x16x32_bf16 v[118:121], v[126:129], v[150:153], v[118:121]
	v_mfma_f32_16x16x32_bf16 v[52:55], v[134:137], v[150:153], v[52:55]
	v_mfma_f32_16x16x32_bf16 v[110:113], v[126:129], v[180:183], v[110:113]
	v_mfma_f32_16x16x32_bf16 v[44:47], v[134:137], v[180:183], v[44:47]
	v_mfma_f32_16x16x32_bf16 v[106:109], v[126:129], v[188:191], v[106:109]
	v_mfma_f32_16x16x32_bf16 v[40:43], v[134:137], v[188:191], v[40:43]
	s_setprio 0
	s_barrier
	s_add_i32 s64, 0, 0x1c000
	s_add_i32 s0, s0, s76
	v_add_u32_e32 v204, s64, v213
	v_lshl_add_u64 v[208:209], v[208:209], 0, s[72:73]
	s_mov_b32 m0, s0
	ds_read_b128 v[192:195], v204
	ds_read_b128 v[196:199], v204 offset:1024
	ds_read_b128 v[200:203], v204 offset:2048
	ds_read_b128 v[204:207], v204 offset:3072
	global_load_lds_dwordx4 v[208:209], off
	v_lshl_add_u64 v[208:209], v[210:211], 0, s[72:73]
	s_add_i32 m0, s0, 0x2000
	s_nop 0
	global_load_lds_dwordx4 v[208:209], off
	s_barrier
	s_waitcnt lgkmcnt(0)
	s_setprio 1
	s_waitcnt lgkmcnt(0)
	v_mfma_f32_16x16x32_bf16 v[154:157], v[192:195], v[138:141], v[154:157]
	v_mfma_f32_16x16x32_bf16 v[56:59], v[200:203], v[138:141], v[56:59]
	v_mfma_f32_16x16x32_bf16 v[114:117], v[192:195], v[146:149], v[114:117]
	v_mfma_f32_16x16x32_bf16 v[48:51], v[200:203], v[146:149], v[48:51]
	v_mfma_f32_16x16x32_bf16 v[102:105], v[192:195], v[176:179], v[102:105]
	v_mfma_f32_16x16x32_bf16 v[36:39], v[200:203], v[176:179], v[36:39]
	v_mfma_f32_16x16x32_bf16 v[98:101], v[192:195], v[184:187], v[98:101]
	v_mfma_f32_16x16x32_bf16 v[32:35], v[200:203], v[184:187], v[32:35]
	v_mfma_f32_16x16x32_bf16 v[154:157], v[196:199], v[142:145], v[154:157]
	v_mfma_f32_16x16x32_bf16 v[56:59], v[204:207], v[142:145], v[56:59]
	v_mfma_f32_16x16x32_bf16 v[114:117], v[196:199], v[150:153], v[114:117]
	v_mfma_f32_16x16x32_bf16 v[48:51], v[204:207], v[150:153], v[48:51]
	v_mfma_f32_16x16x32_bf16 v[102:105], v[196:199], v[180:183], v[102:105]
	v_mfma_f32_16x16x32_bf16 v[36:39], v[204:207], v[180:183], v[36:39]
	v_mfma_f32_16x16x32_bf16 v[98:101], v[196:199], v[188:191], v[98:101]
	v_mfma_f32_16x16x32_bf16 v[32:35], v[204:207], v[188:191], v[32:35]
	s_setprio 0
	s_mov_b32 m0, s89
	v_lshl_add_u64 v[208:209], v[220:221], 0, s[72:73]
	s_barrier
; #define LAS __attribute__((address_space(3)))
; #define PG8_STAGE(bufoff, gbase, voff) do { _Pragma("unroll") for (int _i = 0; _i < 2; ++_i) \
;     __builtin_amdgcn_global_load_lds((const unsigned*)((const char*)(gbase) + (voff)[_i]), (LAS unsigned*)(lds + (bufoff) + ldsw + _i * 8192), 16, 0, 0); } while (0)
; #define PG8_WAIT_V(n) asm volatile("s_waitcnt vmcnt(" #n ")" ::: "memory")
; #define PG8_WAIT_L(n) asm volatile("s_waitcnt lgkmcnt(" #n ")" ::: "memory")
; template <class Epi>
; __device__ __forceinline__ void gemm_phase(LAS unsigned char* lds, const Gemm g, const StaticOrder& S, const Epi& E, int wv0) {
;     ...
;       PG8_LDA(At, 1, 1); PG8_STAGE(PG8_SA(1, 0), a3, voffA);
;       PG8_BAR; PG8_WAIT_L(0); PG8_MMA(1, 0, At, B0); PG8_BAR; PG8_SCHED;
;       PG8_STAGE(PG8_SB(1, 1), b3 + hstepB, voffB);
;       PG8_WAIT_V(6); PG8_BAR; PG8_MMA(1, 1, At, B1); PG8_BAR;
;     }
; __device__ __forceinline__ void epi_upc(const EpiP& e, const f32x4 (&acc)[2][2][4][2], const pg8::Unit& u, int wr, int wc, int fr, int fq) {
;     ...
; #pragma unroll
;   for (int ai = 0; ai < 2; ++ai)
; #pragma unroll
;     for (int m = 0; m < 4; ++m) {
;       const int g = ai * 8 + wr * 4 + m;
; #pragma unroll
;       for (int bj = 0; bj < 2; ++bj) {
;         u32x4 w; w.x = pk2(acc[ai][bj][m][0][0], acc[ai][bj][m][0][1]); w.y = pk2(acc[ai][bj][m][0][2], acc[ai][bj][m][0][3]);
;         w.z = pk2(acc[ai][bj][m][1][0], acc[ai][bj][m][1][1]); w.w = pk2(acc[ai][bj][m][1][2], acc[ai][bj][m][1][3]);
;         if (m == 3 && fr >= 14) *(LAS u32x4*)(ex + ((g * 2 + (fr - 14)) * 256 + bj * 128 + lc0) * 2) = w;
;         const int ucol = bj * DFF + 128 * u.pn + lc0;
;         if (g == 15 && fr >= 14) *(u32x4*)(side + ((size_t)u.pm * 4 + 2 + (fr - 14)) * NUP + ucol) = w;
;         if (g == 0 && fr < 2) *(u32x4*)(side + ((size_t)u.pm * 4 + fr) * NUP + ucol) = w;
;       }
;     }
;   asm volatile("s_waitcnt lgkmcnt(0)" ::: "memory");
;   __builtin_amdgcn_s_barrier();
;   __builtin_amdgcn_s_barrier();
;   asm volatile("" ::: "memory");
;   const float* cw = e.f0; const float* cb = e.f1;
;   bf16_t* act = (bf16_t*)e.out;
; #pragma unroll
;   for (int n = 0; n < 2; ++n) {
;     const int ch = 128 * u.pn + lc0 + 4 * n;
;     const f32x4 wg0 = *(const f32x4*)(cw + ch), wg1 = *(const f32x4*)(cw + NUP + ch), wg2 = *(const f32x4*)(cw + 2 * NUP + ch), bg = *(const f32x4*)(cb + ch);
	ds_read_b128 v[138:141], v225 offset:49152
	ds_read_b128 v[142:145], v225 offset:50176
	ds_read_b128 v[146:149], v225 offset:51200
	ds_read_b128 v[150:153], v225 offset:52224
	ds_read_b128 v[176:179], v225 offset:53248
	ds_read_b128 v[180:183], v225 offset:54272
	ds_read_b128 v[184:187], v225 offset:55296
	ds_read_b128 v[188:191], v225 offset:56320
	global_load_lds_dwordx4 v[208:209], off
	v_lshl_add_u64 v[208:209], v[222:223], 0, s[72:73]
	s_mov_b32 m0, s92
	s_nop 0
	global_load_lds_dwordx4 v[208:209], off
	s_barrier
	s_waitcnt lgkmcnt(0)
	s_setprio 1
	s_waitcnt lgkmcnt(0)
	v_mfma_f32_16x16x32_bf16 v[92:95], v[122:125], v[138:141], v[92:95]
	v_mfma_f32_16x16x32_bf16 v[28:31], v[130:133], v[138:141], v[28:31]
	v_mfma_f32_16x16x32_bf16 v[84:87], v[122:125], v[146:149], v[84:87]
	v_mfma_f32_16x16x32_bf16 v[20:23], v[130:133], v[146:149], v[20:23]
	v_mfma_f32_16x16x32_bf16 v[76:79], v[122:125], v[176:179], v[76:79]
	v_mfma_f32_16x16x32_bf16 v[12:15], v[130:133], v[176:179], v[12:15]
	v_mfma_f32_16x16x32_bf16 v[72:75], v[122:125], v[184:187], v[72:75]
	v_mfma_f32_16x16x32_bf16 v[8:11], v[130:133], v[184:187], v[8:11]
	v_mfma_f32_16x16x32_bf16 v[92:95], v[126:129], v[142:145], v[92:95]
	v_mfma_f32_16x16x32_bf16 v[28:31], v[134:137], v[142:145], v[28:31]
	v_mfma_f32_16x16x32_bf16 v[84:87], v[126:129], v[150:153], v[84:87]
	v_mfma_f32_16x16x32_bf16 v[20:23], v[134:137], v[150:153], v[20:23]
	v_mfma_f32_16x16x32_bf16 v[76:79], v[126:129], v[180:183], v[76:79]
	v_mfma_f32_16x16x32_bf16 v[12:15], v[134:137], v[180:183], v[12:15]
	v_mfma_f32_16x16x32_bf16 v[72:75], v[126:129], v[188:191], v[72:75]
	v_mfma_f32_16x16x32_bf16 v[8:11], v[134:137], v[188:191], v[8:11]
	s_setprio 0
	s_barrier
	s_add_u32 s62, s62, 0x80080
	s_addc_u32 s63, s63, 0
	s_add_i32 s0, s64, s76
	v_lshl_add_u64 v[122:123], s[62:63], 0, v[96:97]
	s_mov_b32 m0, s0
	s_nop 0
	global_load_lds_dwordx4 v[122:123], off
	v_lshl_add_u64 v[122:123], s[62:63], 0, v[166:167]
	s_add_i32 m0, s0, 0x2000
	s_nop 0
	global_load_lds_dwordx4 v[122:123], off
	s_waitcnt vmcnt(6)
	s_barrier
	s_setprio 1
	v_mfma_f32_16x16x32_bf16 v[88:91], v[192:195], v[138:141], v[88:91]
	v_mfma_f32_16x16x32_bf16 v[24:27], v[200:203], v[138:141], v[24:27]
	v_mfma_f32_16x16x32_bf16 v[80:83], v[192:195], v[146:149], v[80:83]
	v_mfma_f32_16x16x32_bf16 v[16:19], v[200:203], v[146:149], v[16:19]
	v_mfma_f32_16x16x32_bf16 v[68:71], v[192:195], v[176:179], v[68:71]
	v_mfma_f32_16x16x32_bf16 v[4:7], v[200:203], v[176:179], v[4:7]
	v_mfma_f32_16x16x32_bf16 v[64:67], v[192:195], v[184:187], v[64:67]
	v_mfma_f32_16x16x32_bf16 v[0:3], v[200:203], v[184:187], v[0:3]
	v_mfma_f32_16x16x32_bf16 v[88:91], v[196:199], v[142:145], v[88:91]
	v_mfma_f32_16x16x32_bf16 v[24:27], v[204:207], v[142:145], v[24:27]
	v_mfma_f32_16x16x32_bf16 v[80:83], v[196:199], v[150:153], v[80:83]
	v_mfma_f32_16x16x32_bf16 v[16:19], v[204:207], v[150:153], v[16:19]
	v_mfma_f32_16x16x32_bf16 v[68:71], v[196:199], v[180:183], v[68:71]
	v_mfma_f32_16x16x32_bf16 v[4:7], v[204:207], v[180:183], v[4:7]
	v_mfma_f32_16x16x32_bf16 v[64:67], v[196:199], v[188:191], v[64:67]
	v_mfma_f32_16x16x32_bf16 v[0:3], v[204:207], v[188:191], v[0:3]
	s_setprio 0
	s_add_i32 s78, s78, 2
	s_add_u32 s60, s60, 0x100
	s_addc_u32 s61, s61, 0
	s_add_u32 s59, s59, 0x100
	s_addc_u32 s75, s75, 0
	s_cmp_gt_u32 s78, 29
	s_barrier
	s_cbranch_scc0 .LBB0_1270
	s_lshl_b32 s100, s58, 7
	v_or_b32_e32 v230, s100, v214
	v_lshlrev_b32_e32 v230, 2, v230
	s_mov_b32 s101, 0
	global_load_dwordx4 v[182:185], v230, s[16:17]
	global_load_dwordx4 v[186:189], v230, s[20:21]
	global_load_dwordx4 v[190:193], v230, s[22:23]
	global_load_dwordx4 v[194:197], v230, s[18:19]
	global_load_dwordx4 v[198:201], v230, s[24:25]
	global_load_dwordx4 v[202:205], v230, s[30:31]
	global_load_dwordx4 v[206:209], v230, s[26:27]
	global_load_dwordx4 v[220:223], v230, s[28:29]
	s_and_saveexec_b64 s[60:61], s[36:37]
	s_movk_i32 s78, 0x5800
	s_cbranch_execz .LBB0_1273
	s_ashr_i32 s57, s56, 31
	s_lshl_b64 s[0:1], s[56:57], 2
	s_lshl_b32 s49, s58, 7
	v_or_b32_e32 v127, s0, v168
	v_mov_b64_e32 v[128:129], s[14:15]
	v_or_b32_e32 v126, s49, v214
	v_mad_u64_u32 v[128:129], s[62:63], v127, s78, v[128:129]
	v_mov_b32_e32 v127, 0x5800
	v_mad_i32_i24 v129, s1, v127, v129
	v_ashrrev_i32_e32 v127, 31, v126
	v_cvt_pk_bf16_f32 v122, v158, v159
	v_cvt_pk_bf16_f32 v123, v160, v161
	v_cvt_pk_bf16_f32 v124, v60, v61
	v_cvt_pk_bf16_f32 v125, v62, v63
	v_lshl_add_u64 v[126:127], v[126:127], 1, v[128:129]
	global_store_dwordx4 v[126:127], v[122:125], off
	s_addk_i32 s101, 1
	v_add_u32_e32 v126, s49, v169
	v_ashrrev_i32_e32 v127, 31, v126
	v_cvt_pk_bf16_f32 v122, v154, v155
	v_cvt_pk_bf16_f32 v123, v156, v157
	v_cvt_pk_bf16_f32 v124, v56, v57
	v_cvt_pk_bf16_f32 v125, v58, v59
	v_lshl_add_u64 v[126:127], v[126:127], 1, v[128:129]
	global_store_dwordx4 v[126:127], v[122:125], off
	s_addk_i32 s101, 1
.LBB0_1273:
	s_or_b64 exec, exec, s[60:61]
	s_nop 0
	v_cvt_pk_bf16_f32 v122, v106, v107
	v_cvt_pk_bf16_f32 v123, v108, v109
	v_cvt_pk_bf16_f32 v124, v40, v41
	v_cvt_pk_bf16_f32 v125, v42, v43
	s_and_saveexec_b64 s[60:61], s[2:3]
	ds_write_b128 v217, v[122:125]
	s_or_b64 exec, exec, s[60:61]
	v_lshl_or_b32 v126, s58, 7, v214
	s_and_saveexec_b64 s[60:61], s[40:41]
	s_cbranch_execz .LBB0_1277
	s_ashr_i32 s57, s56, 31
	v_lshl_add_u64 v[128:129], s[56:57], 2, v[170:171]
	v_mov_b64_e32 v[130:131], s[14:15]
	v_mad_u64_u32 v[130:131], s[0:1], v128, s78, v[130:131]
	v_mad_i32_i24 v131, v129, s78, v131
	v_ashrrev_i32_e32 v127, 31, v126
	v_lshl_add_u64 v[128:129], v[126:127], 1, v[130:131]
	global_store_dwordx4 v[128:129], v[122:125], off
	s_addk_i32 s101, 1

; #define LAS __attribute__((address_space(3)))
; __device__ __forceinline__ void epi_upc(const EpiP& e, const f32x4 (&acc)[2][2][4][2], const pg8::Unit& u, int wr, int wc, int fr, int fq) {
;     ...
;         u32x4 w; w.x = pk2(acc[ai][bj][m][0][0], acc[ai][bj][m][0][1]); w.y = pk2(acc[ai][bj][m][0][2], acc[ai][bj][m][0][3]);
;         w.z = pk2(acc[ai][bj][m][1][0], acc[ai][bj][m][1][1]); w.w = pk2(acc[ai][bj][m][1][2], acc[ai][bj][m][1][3]);
;         if (m == 3 && fr >= 14) *(LAS u32x4*)(ex + ((g * 2 + (fr - 14)) * 256 + bj * 128 + lc0) * 2) = w;
;         const int ucol = bj * DFF + 128 * u.pn + lc0;
;         if (g == 15 && fr >= 14) *(u32x4*)(side + ((size_t)u.pm * 4 + 2 + (fr - 14)) * NUP + ucol) = w;
;         if (g == 0 && fr < 2) *(u32x4*)(side + ((size_t)u.pm * 4 + fr) * NUP + ucol) = w;
;       }
;     }
;   asm volatile("s_waitcnt lgkmcnt(0)" ::: "memory");
;   __builtin_amdgcn_s_barrier();
;   __builtin_amdgcn_s_barrier();
;   asm volatile("" ::: "memory");
;   const float* cw = e.f0; const float* cb = e.f1;
;   bf16_t* act = (bf16_t*)e.out;
; #pragma unroll
;   for (int n = 0; n < 2; ++n) {
;     const int ch = 128 * u.pn + lc0 + 4 * n;
;     const f32x4 wg0 = *(const f32x4*)(cw + ch), wg1 = *(const f32x4*)(cw + NUP + ch), wg2 = *(const f32x4*)(cw + 2 * NUP + ch), bg = *(const f32x4*)(cb + ch);
;     const f32x4 wv0 = *(const f32x4*)(cw + DFF + ch), wv1 = *(const f32x4*)(cw + NUP + DFF + ch), wv2 = *(const f32x4*)(cw + 2 * NUP + DFF + ch), bv = *(const f32x4*)(cb + DFF + ch);
.LBB0_1280:
	s_ashr_i32 s57, s56, 31
	s_lshl_b64 s[0:1], s[56:57], 2
	s_lshl_b32 s49, s58, 7
	v_or_b32_e32 v127, s0, v168
	v_mov_b64_e32 v[130:131], s[14:15]
	v_or_b32_e32 v128, s49, v214
	v_mad_u64_u32 v[130:131], s[62:63], v127, s78, v[130:131]
	v_mov_b32_e32 v127, 0x5800
	v_mad_i32_i24 v131, s1, v127, v131
	v_ashrrev_i32_e32 v129, 31, v128
	v_cvt_pk_bf16_f32 v122, v92, v93
	v_cvt_pk_bf16_f32 v123, v94, v95
	v_cvt_pk_bf16_f32 v124, v28, v29
	v_cvt_pk_bf16_f32 v125, v30, v31
	v_lshl_add_u64 v[128:129], v[128:129], 1, v[130:131]
	global_store_dwordx4 v[128:129], v[122:125], off
	s_addk_i32 s101, 1
	v_add_u32_e32 v128, s49, v169
	v_ashrrev_i32_e32 v129, 31, v128
	v_cvt_pk_bf16_f32 v122, v88, v89
	v_cvt_pk_bf16_f32 v123, v90, v91
	v_cvt_pk_bf16_f32 v124, v24, v25
	v_cvt_pk_bf16_f32 v125, v26, v27
	v_lshl_add_u64 v[128:129], v[128:129], 1, v[130:131]
	global_store_dwordx4 v[128:129], v[122:125], off
	s_addk_i32 s101, 1
.LBB0_1281:
	s_or_b64 exec, exec, s[60:61]
	s_nop 0
	v_cvt_pk_bf16_f32 v122, v72, v73
	v_cvt_pk_bf16_f32 v123, v74, v75
	v_cvt_pk_bf16_f32 v124, v8, v9
	v_cvt_pk_bf16_f32 v125, v10, v11
	s_and_saveexec_b64 s[60:61], s[2:3]
	ds_write_b128 v253, v[122:125]
	s_or_b64 exec, exec, s[60:61]
	s_and_saveexec_b64 s[60:61], s[46:47]
	s_cbranch_execz .LBB0_1285
	s_ashr_i32 s57, s56, 31
	v_lshl_add_u64 v[128:129], s[56:57], 2, v[170:171]
	v_mov_b64_e32 v[130:131], s[14:15]
	v_mad_u64_u32 v[130:131], s[0:1], v128, s78, v[130:131]
	v_mad_i32_i24 v131, v129, s78, v131
	v_ashrrev_i32_e32 v127, 31, v126
	v_lshl_add_u64 v[126:127], v[126:127], 1, v[130:131]
	global_store_dwordx4 v[126:127], v[122:125], off
	s_addk_i32 s101, 1
.LBB0_1285:
	s_or_b64 exec, exec, s[60:61]
	s_nop 0
	v_cvt_pk_bf16_f32 v122, v64, v65
	v_cvt_pk_bf16_f32 v123, v66, v67
	v_cvt_pk_bf16_f32 v124, v0, v1
	v_cvt_pk_bf16_f32 v125, v2, v3
	s_and_saveexec_b64 s[60:61], s[2:3]
	ds_write_b128 v224, v[122:125]
	s_or_b64 exec, exec, s[60:61]
	s_lshl_b32 s0, s58, 7
	s_and_saveexec_b64 s[58:59], s[46:47]
	s_cbranch_execz .LBB0_1289
	s_ashr_i32 s57, s56, 31
	v_lshl_add_u64 v[128:129], s[56:57], 2, v[170:171]
	v_mov_b64_e32 v[130:131], s[14:15]
	v_add_u32_e32 v126, s0, v169
	v_mad_u64_u32 v[130:131], s[60:61], v128, s78, v[130:131]
	v_mad_i32_i24 v131, v129, s78, v131
	v_ashrrev_i32_e32 v127, 31, v126
	v_lshl_add_u64 v[126:127], v[126:127], 1, v[130:131]
	global_store_dwordx4 v[126:127], v[122:125], off
	s_addk_i32 s101, 1
.LBB0_1289:
	s_or_b64 exec, exec, s[58:59]
	v_or_b32_e32 v176, s0, v214
	v_ashrrev_i32_e32 v177, 31, v176
	v_lshlrev_b64 v[134:135], 2, v[176:177]
	s_waitcnt lgkmcnt(0)
	s_barrier
	s_barrier
	v_lshl_add_u64 v[178:179], s[16:17], 0, v[134:135]
	v_lshl_add_u64 v[122:123], s[20:21], 0, v[134:135]
	v_lshl_add_u64 v[124:125], s[22:23], 0, v[134:135]
	v_lshl_add_u64 v[180:181], s[18:19], 0, v[134:135]
	v_lshl_add_u64 v[122:123], s[24:25], 0, v[134:135]
	v_lshl_add_u64 v[126:127], s[30:31], 0, v[134:135]
	v_lshl_add_u64 v[130:131], s[26:27], 0, v[134:135]
	v_lshl_add_u64 v[134:135], s[28:29], 0, v[134:135]
	v_mov_b32_dpp v238, v158 row_shr:1 row_mask:0xf bank_mask:0xf bound_ctrl:1
	v_mov_b32_dpp v239, v158 row_shr:2 row_mask:0xf bank_mask:0xf bound_ctrl:1
	v_mov_b32_dpp v241, v154 row_shr:1 row_mask:0xf bank_mask:0xf bound_ctrl:1
	v_mov_b32_dpp v240, v154 row_shr:2 row_mask:0xf bank_mask:0xf bound_ctrl:1
	v_mov_b32_dpp v235, v159 row_shr:1 row_mask:0xf bank_mask:0xf bound_ctrl:1
	v_mov_b32_dpp v232, v159 row_shr:2 row_mask:0xf bank_mask:0xf bound_ctrl:1
	v_mov_b32_dpp v237, v155 row_shr:1 row_mask:0xf bank_mask:0xf bound_ctrl:1
	v_mov_b32_dpp v236, v155 row_shr:2 row_mask:0xf bank_mask:0xf bound_ctrl:1
	v_mov_b32_dpp v229, v160 row_shr:1 row_mask:0xf bank_mask:0xf bound_ctrl:1
	v_mov_b32_dpp v227, v160 row_shr:2 row_mask:0xf bank_mask:0xf bound_ctrl:1
	v_mov_b32_dpp v234, v156 row_shr:1 row_mask:0xf bank_mask:0xf bound_ctrl:1
	v_mov_b32_dpp v233, v156 row_shr:2 row_mask:0xf bank_mask:0xf bound_ctrl:1
	v_mov_b32_dpp v228, v161 row_shr:1 row_mask:0xf bank_mask:0xf bound_ctrl:1
	v_mov_b32_dpp v226, v161 row_shr:2 row_mask:0xf bank_mask:0xf bound_ctrl:1
	v_mov_b32_dpp v231, v157 row_shr:1 row_mask:0xf bank_mask:0xf bound_ctrl:1
	v_mov_b32_dpp v230, v157 row_shr:2 row_mask:0xf bank_mask:0xf bound_ctrl:1
	s_cmp_lg_u32 s101, 0
	s_cbranch_scc1 .Lupw1
	s_waitcnt vmcnt(0)
	s_branch .Lupwd
.Lupw1:
	s_cmp_lg_u32 s101, 1
	s_cbranch_scc1 .Lupw2
	s_waitcnt vmcnt(1)
	s_branch .Lupwd
.Lupw2:
	s_cmp_lg_u32 s101, 2
	s_cbranch_scc1 .Lupw3
	s_waitcnt vmcnt(2)
	s_branch .Lupwd
.Lupw3:
	s_cmp_lg_u32 s101, 3
	s_cbranch_scc1 .Lupw4
	s_waitcnt vmcnt(3)
	s_branch .Lupwd
.Lupw4:
	s_cmp_lg_u32 s101, 4
	s_cbranch_scc1 .Lupw5
	s_waitcnt vmcnt(4)
	s_branch .Lupwd
.Lupw5:
	s_cmp_lg_u32 s101, 5
	s_cbranch_scc1 .Lupw6
	s_waitcnt vmcnt(5)
	s_branch .Lupwd
.Lupw6:
	s_cmp_lg_u32 s101, 6
	s_cbranch_scc1 .Lupw7
	s_waitcnt vmcnt(6)
	s_branch .Lupwd
.Lupw7:
	s_cmp_lg_u32 s101, 7
	s_cbranch_scc1 .Lupw8
	s_waitcnt vmcnt(7)
	s_branch .Lupwd
.Lupw8:
	s_waitcnt vmcnt(8)
; __device__ __forceinline__ void epi_upc(const EpiP& e, const f32x4 (&acc)[2][2][4][2], const pg8::Unit& u, int wr, int wc, int fr, int fq) {
;     ...
;     const f32x4 wg0 = *(const f32x4*)(cw + ch), wg1 = *(const f32x4*)(cw + NUP + ch), wg2 = *(const f32x4*)(cw + 2 * NUP + ch), bg = *(const f32x4*)(cb + ch);
;     const f32x4 wv0 = *(const f32x4*)(cw + DFF + ch), wv1 = *(const f32x4*)(cw + NUP + DFF + ch), wv2 = *(const f32x4*)(cw + 2 * NUP + DFF + ch), bv = *(const f32x4*)(cb + DFF + ch);
; #pragma unroll
;     for (int ai = 0; ai < 2; ++ai)
; #pragma unroll
;       for (int m = 0; m < 4; ++m) {
;         const int g = ai * 8 + wr * 4 + m, gp = g > 0 ? g - 1 : 0;
;         const f32x4 xg = acc[ai][0][m][n], xv = acc[ai][1][m][n];
;         float y[4];
;         if (m > 0) {
;           const f32x4 pg = acc[ai][0][m - 1][n], pv = acc[ai][1][m - 1][n];
; #pragma unroll
;           for (int k = 0; k < 4; ++k) {
;             const float g1 = dpp_prev1(pg[k], xg[k]), g2 = dpp_prev2(pg[k], xg[k]), v1 = dpp_prev1(pv[k], xv[k]), v2 = dpp_prev2(pv[k], xv[k]);
;             const float cg = bg[k] + wg0[k] * g2 + wg1[k] * g1 + wg2[k] * xg[k];
;             const float cv = bv[k] + wv0[k] * v2 + wv1[k] * v1 + wv2[k] * xv[k];
;             y[k] = silu_mul(cg, cv);
;           }
;         } else {
;           const LAS unsigned char* hp = ex + (gp * 2 * 256 + lc0 + 4 * n) * 2;
;           const u32x2 hg14 = *(const LAS u32x2*)hp, hg15 = *(const LAS u32x2*)(hp + 512), hv14 = *(const LAS u32x2*)(hp + 256), hv15 = *(const LAS u32x2*)(hp + 512 + 256);
;           const float h14g[4] = {bf_lo(hg14.x), bf_hi(hg14.x), bf_lo(hg14.y), bf_hi(hg14.y)}, h15g[4] = {bf_lo(hg15.x), bf_hi(hg15.x), bf_lo(hg15.y), bf_hi(hg15.y)};
;           const float h14v[4] = {bf_lo(hv14.x), bf_hi(hv14.x), bf_lo(hv14.y), bf_hi(hv14.y)}, h15v[4] = {bf_lo(hv15.x), bf_hi(hv15.x), bf_lo(hv15.y), bf_hi(hv15.y)};
; #pragma unroll
;           for (int k = 0; k < 4; ++k) {
;             float g1 = dpp_shr1(xg[k]), g2 = dpp_shr2(xg[k]), v1 = dpp_shr1(xv[k]), v2 = dpp_shr2(xv[k]);
;             if (fr == 0) { g1 = h15g[k]; g2 = h14g[k]; v1 = h15v[k]; v2 = h14v[k]; }
;             if (fr == 1) { g2 = h15g[k]; v2 = h15v[k]; }
;             const float cg = bg[k] + wg0[k] * g2 + wg1[k] * g1 + wg2[k] * xg[k];
;             const float cv = bv[k] + wv0[k] * v2 + wv1[k] * v1 + wv2[k] * xv[k];
.Lupwd:
	v_mov_b64_e32 v[138:139], v[182:183]
	v_mov_b64_e32 v[140:141], v[184:185]
	v_mov_b64_e32 v[142:143], v[186:187]
	v_mov_b64_e32 v[144:145], v[188:189]
	v_mov_b64_e32 v[146:147], v[190:191]
	v_mov_b64_e32 v[148:149], v[192:193]
	v_mov_b64_e32 v[150:151], v[194:195]
	v_mov_b64_e32 v[152:153], v[196:197]
	v_mov_b64_e32 v[122:123], v[198:199]
	v_mov_b64_e32 v[124:125], v[200:201]
	v_mov_b64_e32 v[126:127], v[202:203]
	v_mov_b64_e32 v[128:129], v[204:205]
	v_mov_b64_e32 v[130:131], v[206:207]
	v_mov_b64_e32 v[132:133], v[208:209]
	v_mov_b64_e32 v[134:135], v[220:221]
	v_mov_b64_e32 v[136:137], v[222:223]
	v_lshl_add_u64 v[182:183], v[176:177], 1, s[12:13]
	v_mov_b32_e32 v204, v138
	v_mov_b32_e32 v208, v142
	v_mov_b32_e32 v210, v146
	v_mov_b32_e32 v197, v139
	v_mov_b32_e32 v201, v143
	v_mov_b32_e32 v203, v147
	v_mov_b32_e32 v187, v140
	v_mov_b32_e32 v193, v144
	v_mov_b32_e32 v206, v150
	v_mov_b32_e32 v199, v151
	v_mov_b32_e32 v205, v122
	v_mov_b32_e32 v196, v123
	v_mov_b32_e32 v207, v126
	v_mov_b32_e32 v198, v127
	v_mov_b32_e32 v209, v130
	v_mov_b32_e32 v200, v131
	v_mov_b32_e32 v211, v134
	v_mov_b32_e32 v202, v135
	v_mov_b32_e32 v186, v124
	v_mov_b32_e32 v190, v128
	v_mov_b32_e32 v191, v152
	v_mov_b32_e32 v192, v132
	v_mov_b32_e32 v194, v136
	v_mov_b32_e32 v195, v148
	v_mov_b32_e32 v184, v149
	v_mov_b32_e32 v185, v137
	v_mov_b32_e32 v188, v145
	v_mov_b32_e32 v189, v133
	s_and_saveexec_b64 s[58:59], s[38:39]
	s_xor_b64 s[58:59], exec, s[58:59]
	s_cbranch_execz .LBB0_1291
	v_add_u32_e32 v177, s35, v215
	v_mov_b64_e32 v[218:219], v[244:245]
	ds_read2_b64 v[242:245], v177 offset1:32
	ds_read2_b64 v[220:223], v177 offset0:64 offset1:96
	s_lshl_b32 s0, s56, 8
	s_waitcnt lgkmcnt(0)
	v_and_b32_e32 v177, 0xffff0000, v242
	v_and_b32_e32 v248, 0xffff0000, v244
	v_lshlrev_b32_e32 v188, 16, v220
	v_lshlrev_b32_e32 v244, 16, v244
	v_lshlrev_b32_e32 v242, 16, v242
	v_lshlrev_b32_e32 v189, 16, v222
	v_cndmask_b32_e64 v184, v238, v188, s[4:5]
	v_cndmask_b32_e64 v238, v239, v242, s[4:5]
	v_cndmask_b32_e64 v239, v240, v244, s[4:5]
	v_cndmask_b32_e64 v185, v241, v189, s[4:5]
	v_cndmask_b32_e64 v189, v239, v189, s[6:7]
	v_cndmask_b32_e64 v188, v238, v188, s[6:7]
	v_pk_fma_f32 v[188:189], v[204:205], v[188:189], v[206:207]
	v_and_b32_e32 v220, 0xffff0000, v220
	v_pk_fma_f32 v[184:185], v[208:209], v[184:185], v[188:189]
	v_mov_b32_e32 v188, v158
	v_mov_b32_e32 v189, v154
	v_pk_fma_f32 v[184:185], v[188:189], v[210:211], v[184:185]
	v_and_b32_e32 v222, 0xffff0000, v222
	v_mul_f32_e32 v188, 0xbfb8aa3b, v184
	v_exp_f32_e32 v188, v188
	v_cndmask_b32_e64 v189, v235, v220, s[4:5]
	v_cndmask_b32_e64 v235, v236, v248, s[4:5]
	v_cndmask_b32_e64 v177, v232, v177, s[4:5]
	v_add_f32_e32 v188, 1.0, v188
	v_lshlrev_b32_e32 v239, 16, v221
	v_and_b32_e32 v240, 0xffff0000, v221
	v_rcp_f32_e32 v241, v188
	v_cndmask_b32_e64 v221, v177, v220, s[6:7]
	v_cndmask_b32_e64 v220, v235, v222, s[6:7]
	v_cndmask_b32_e64 v188, v237, v222, s[4:5]
	v_pk_fma_f32 v[220:221], v[196:197], v[220:221], v[198:199]
	v_lshlrev_b32_e32 v249, 16, v243
	v_lshlrev_b32_e32 v252, 16, v245
	v_pk_fma_f32 v[188:189], v[200:201], v[188:189], v[220:221]
	v_mov_b32_e32 v220, v155
	v_mov_b32_e32 v221, v159
	v_lshlrev_b32_e32 v238, 16, v223
	v_pk_fma_f32 v[188:189], v[220:221], v[202:203], v[188:189]
	v_cndmask_b32_e64 v220, v233, v252, s[4:5]
	v_cndmask_b32_e64 v221, v227, v249, s[4:5]
	v_mul_f32_e32 v184, v184, v241
	v_cndmask_b32_e64 v221, v221, v239, s[6:7]
	v_cndmask_b32_e64 v220, v220, v238, s[6:7]
	v_mul_f32_e32 v236, v185, v184
	v_cndmask_b32_e64 v185, v229, v239, s[4:5]
	v_cndmask_b32_e64 v184, v234, v238, s[4:5]
	v_pk_fma_f32 v[220:221], v[186:187], v[220:221], v[190:191]
	v_and_b32_e32 v243, 0xffff0000, v243
	v_pk_fma_f32 v[184:185], v[192:193], v[184:185], v[220:221]
	v_mov_b32_e32 v220, v156
	v_mov_b32_e32 v221, v160
	v_pk_fma_f32 v[184:185], v[220:221], v[194:195], v[184:185]
	v_and_b32_e32 v245, 0xffff0000, v245
	v_mul_f32_e32 v177, 0xbfb8aa3b, v189
	v_and_b32_e32 v232, 0xffff0000, v223
	v_mul_f32_e32 v220, 0xbfb8aa3b, v185
	v_exp_f32_e32 v177, v177
	v_exp_f32_e32 v237, v220
	v_cndmask_b32_e64 v220, v231, v232, s[4:5]
	v_cndmask_b32_e64 v230, v230, v245, s[4:5]
	v_cndmask_b32_e64 v231, v226, v243, s[4:5]
	v_cndmask_b32_e64 v231, v231, v240, s[6:7]
	v_cndmask_b32_e64 v230, v230, v232, s[6:7]
	v_mov_b32_e32 v232, v125
	v_mov_b32_e32 v233, v141
	v_mov_b32_e32 v234, v129
	v_mov_b32_e32 v235, v153
	v_cndmask_b32_e64 v221, v228, v240, s[4:5]
	v_mov_b32_e32 v228, v133
	v_mov_b32_e32 v229, v145
	v_pk_fma_f32 v[230:231], v[232:233], v[230:231], v[234:235]
	v_mov_b32_e32 v222, v157
	v_mov_b32_e32 v223, v161
	v_mov_b32_e32 v226, v137
	v_mov_b32_e32 v227, v149
	v_pk_fma_f32 v[220:221], v[228:229], v[220:221], v[230:231]
	v_add_f32_e32 v177, 1.0, v177
	v_pk_fma_f32 v[220:221], v[222:223], v[226:227], v[220:221]
	v_rcp_f32_e32 v177, v177
	v_mul_f32_e32 v222, 0xbfb8aa3b, v221
	v_exp_f32_e32 v222, v222
	v_mov_b64_e32 v[244:245], v[218:219]
	v_mul_f32_e32 v177, v189, v177
	v_add_f32_e32 v189, 1.0, v237
	v_rcp_f32_e32 v189, v189
	v_add_f32_e32 v222, 1.0, v222
	v_rcp_f32_e32 v222, v222
	v_mul_f32_e32 v177, v188, v177
	v_mul_f32_e32 v185, v185, v189
	v_mul_f32_e32 v185, v184, v185
	v_mul_f32_e32 v184, v221, v222
	v_mul_f32_e32 v188, v220, v184
	v_add_u32_e32 v189, s0, v212
	v_cvt_pk_bf16_f32 v184, v236, v177
	v_cvt_pk_bf16_f32 v185, v185, v188
	v_mad_i64_i32 v[188:189], s[60:61], v189, s74, v[182:183]
	global_store_dwordx2 v[188:189], v[184:185], off
	v_mov_b32_e32 v184, v149
	v_mov_b32_e32 v185, v137
	v_mov_b32_e32 v188, v145
	v_mov_b32_e32 v189, v133

; __device__ __forceinline__ void epi_upc(const EpiP& e, const f32x4 (&acc)[2][2][4][2], const pg8::Unit& u, int wr, int wc, int fr, int fq) {
;     ...
;         if (g == 15 && fr >= 14) *(u32x4*)(side + ((size_t)u.pm * 4 + 2 + (fr - 14)) * NUP + ucol) = w;
;         if (g == 0 && fr < 2) *(u32x4*)(side + ((size_t)u.pm * 4 + fr) * NUP + ucol) = w;
.LBB0_1300:
	s_ashr_i32 s57, s56, 31
	v_lshl_add_u64 v[130:131], s[56:57], 2, v[170:171]
	v_mov_b64_e32 v[132:133], s[14:15]
	v_lshl_add_u32 v128, s58, 7, v169
	v_mad_u64_u32 v[132:133], s[0:1], v130, s78, v[132:133]
	v_mad_i32_i24 v133, v131, s78, v133
	v_ashrrev_i32_e32 v129, 31, v128
	v_lshl_add_u64 v[128:129], v[128:129], 1, v[132:133]
	global_store_dwordx4 v[128:129], v[122:125], off
	s_addk_i32 s101, 1
	s_or_b64 exec, exec, s[60:61]
	s_and_saveexec_b64 s[60:61], s[42:43]
	s_cbranch_execnz .LBB0_1280
	s_branch .LBB0_1281
